# QK-norm epilogue: row-scale multiplies packed (v_pk_mul_f32 with op_sel broadcast), on top of v11
# baseline (speedup 1.0000x reference)
; __device__ __forceinline__ float rstd_of(float ss) { return rsqrtf(ss * (1.0f / DM) + EPS); }
; __device__ __forceinline__ void unpack8(const u32x4 w, f32x4& a, f32x4& b) { a[0] = bf_lo(w.x); a[1] = bf_hi(w.x); a[2] = bf_lo(w.y); a[3] = bf_hi(w.y); b[0] = bf_lo(w.z); b[1] = bf_hi(w.z); b[2] = bf_lo(w.w); b[3] = bf_hi(w.w); }
;     __device__ __forceinline__ void operator()(const AccT& acc, const Unit& u, int wr, int wc, int fr, int fq) const {
;     ...
;                         const float rs = rstd_of(rsv[ai][m]);
;                         f32x4 v0 = acc[ai][bj][m][0] * rs, v1 = acc[ai][bj][m][1] * rs;
; __device__ void ph_qknorm(bf16_t* Z, const float* qg, const float* kg, const int WID) {
;     ...
;             f32x4 a0, a1, a2, a3; unpack8(w0[q], a0, a1); unpack8(w1[q], a2, a3);
;             float ss = 0.f;
; #pragma unroll
;             for (int j = 0; j < 4; ++j) ss += a0[j] * a0[j] + a1[j] * a1[j] + a2[j] * a2[j] + a3[j] * a3[j];
.Lqk_g:
	v_readlane_b32 s18, v255, 4
	v_readlane_b32 s19, v255, 5
	v_lshlrev_b32_e32 v161, 2, v175
	v_xor_b32_e32 v164, 16, v248
	v_xor_b32_e32 v165, 32, v248
	s_and_b64 s[18:19], s[18:19], exec
	s_cselect_b32 s18, 0x200, 0
	s_add_u32 s0, s0, s18
	s_addc_u32 s1, s1, 0
	v_lshlrev_b32_e32 v164, 2, v164
	v_lshlrev_b32_e32 v165, 2, v165
	v_lshrrev_b32_e32 v166, 5, v175
	v_and_b32_e32 v166, 3, v166
	v_lshlrev_b32_e32 v167, 5, v1
	global_load_dwordx4 v[138:141], v161, s[0:1]
	global_load_dwordx4 v[142:145], v161, s[0:1] offset:16
	v_add_u32_e32 v167, 0x20000, v167
	v_lshl_add_u32 v166, v166, 2, v167
	v_mul_u32_u24_e32 v163, 0x4800, v160
	v_lshl_add_u32 v163, v158, 1, v163
	s_waitcnt vmcnt(2)
	v_fmamk_f32 v130, v130, 0x3a000000, v251
	v_fmamk_f32 v131, v131, 0x3a000000, v251
	v_fmamk_f32 v132, v132, 0x3a000000, v251
	v_fmamk_f32 v133, v133, 0x3a000000, v251
	v_fmamk_f32 v134, v134, 0x3a000000, v251
	v_fmamk_f32 v135, v135, 0x3a000000, v251
	v_fmamk_f32 v136, v136, 0x3a000000, v251
	v_fmamk_f32 v137, v137, 0x3a000000, v251
	v_rsq_f32_e32 v130, v130
	v_rsq_f32_e32 v131, v131
	v_rsq_f32_e32 v132, v132
	v_rsq_f32_e32 v133, v133
	v_rsq_f32_e32 v134, v134
	v_rsq_f32_e32 v135, v135
	v_rsq_f32_e32 v136, v136
	v_rsq_f32_e32 v137, v137
	v_pk_mul_f32 v[126:127], v[126:127], v[130:131] op_sel_hi:[1,0]
	v_pk_mul_f32 v[128:129], v[128:129], v[130:131] op_sel_hi:[1,0]
	v_pk_mul_f32 v[122:123], v[122:123], v[130:131] op_sel_hi:[1,0]
	v_pk_mul_f32 v[124:125], v[124:125], v[130:131] op_sel_hi:[1,0]
	v_mul_f32_e32 v178, v126, v126
	v_fmac_f32_e32 v178, v127, v127
	v_fmac_f32_e32 v178, v128, v128
	v_fmac_f32_e32 v178, v129, v129
	v_fmac_f32_e32 v178, v122, v122
	v_fmac_f32_e32 v178, v123, v123
	v_fmac_f32_e32 v178, v124, v124
	v_fmac_f32_e32 v178, v125, v125
	v_pk_mul_f32 v[62:63], v[62:63], v[130:131] op_sel_hi:[1,0]
	v_pk_mul_f32 v[64:65], v[64:65], v[130:131] op_sel_hi:[1,0]
	v_pk_mul_f32 v[58:59], v[58:59], v[130:131] op_sel_hi:[1,0]
	v_pk_mul_f32 v[60:61], v[60:61], v[130:131] op_sel_hi:[1,0]
	v_mul_f32_e32 v179, v62, v62
	v_fmac_f32_e32 v179, v63, v63
	v_fmac_f32_e32 v179, v64, v64
	v_fmac_f32_e32 v179, v65, v65
	v_fmac_f32_e32 v179, v58, v58
	v_fmac_f32_e32 v179, v59, v59
	v_fmac_f32_e32 v179, v60, v60
	v_fmac_f32_e32 v179, v61, v61
	v_pk_mul_f32 v[118:119], v[118:119], v[130:131] op_sel:[0,1] op_sel_hi:[1,1]
	v_pk_mul_f32 v[120:121], v[120:121], v[130:131] op_sel:[0,1] op_sel_hi:[1,1]
	v_pk_mul_f32 v[114:115], v[114:115], v[130:131] op_sel:[0,1] op_sel_hi:[1,1]
	v_pk_mul_f32 v[116:117], v[116:117], v[130:131] op_sel:[0,1] op_sel_hi:[1,1]
	v_mul_f32_e32 v180, v118, v118
	v_fmac_f32_e32 v180, v119, v119
	v_fmac_f32_e32 v180, v120, v120
	v_fmac_f32_e32 v180, v121, v121
	v_fmac_f32_e32 v180, v114, v114
	v_fmac_f32_e32 v180, v115, v115
	v_fmac_f32_e32 v180, v116, v116
	v_fmac_f32_e32 v180, v117, v117
	v_pk_mul_f32 v[54:55], v[54:55], v[130:131] op_sel:[0,1] op_sel_hi:[1,1]
	v_pk_mul_f32 v[56:57], v[56:57], v[130:131] op_sel:[0,1] op_sel_hi:[1,1]
	v_pk_mul_f32 v[50:51], v[50:51], v[130:131] op_sel:[0,1] op_sel_hi:[1,1]
	v_pk_mul_f32 v[52:53], v[52:53], v[130:131] op_sel:[0,1] op_sel_hi:[1,1]
	v_mul_f32_e32 v181, v54, v54
	v_fmac_f32_e32 v181, v55, v55
	v_fmac_f32_e32 v181, v56, v56
	v_fmac_f32_e32 v181, v57, v57
	v_fmac_f32_e32 v181, v50, v50
	v_fmac_f32_e32 v181, v51, v51
	v_fmac_f32_e32 v181, v52, v52
	v_fmac_f32_e32 v181, v53, v53
	v_pk_mul_f32 v[110:111], v[110:111], v[132:133] op_sel_hi:[1,0]
	v_pk_mul_f32 v[112:113], v[112:113], v[132:133] op_sel_hi:[1,0]
	v_pk_mul_f32 v[106:107], v[106:107], v[132:133] op_sel_hi:[1,0]
	v_pk_mul_f32 v[108:109], v[108:109], v[132:133] op_sel_hi:[1,0]
	v_mul_f32_e32 v182, v110, v110
	v_fmac_f32_e32 v182, v111, v111
	v_fmac_f32_e32 v182, v112, v112
	v_fmac_f32_e32 v182, v113, v113
	v_fmac_f32_e32 v182, v106, v106
	v_fmac_f32_e32 v182, v107, v107
	v_fmac_f32_e32 v182, v108, v108
	v_fmac_f32_e32 v182, v109, v109
	v_pk_mul_f32 v[46:47], v[46:47], v[132:133] op_sel_hi:[1,0]
	v_pk_mul_f32 v[48:49], v[48:49], v[132:133] op_sel_hi:[1,0]
	v_pk_mul_f32 v[42:43], v[42:43], v[132:133] op_sel_hi:[1,0]
	v_pk_mul_f32 v[44:45], v[44:45], v[132:133] op_sel_hi:[1,0]
	v_mul_f32_e32 v183, v46, v46
	v_fmac_f32_e32 v183, v47, v47
	v_fmac_f32_e32 v183, v48, v48
	v_fmac_f32_e32 v183, v49, v49
	v_fmac_f32_e32 v183, v42, v42
	v_fmac_f32_e32 v183, v43, v43
	v_fmac_f32_e32 v183, v44, v44
	v_fmac_f32_e32 v183, v45, v45
	v_pk_mul_f32 v[102:103], v[102:103], v[132:133] op_sel:[0,1] op_sel_hi:[1,1]
	v_pk_mul_f32 v[104:105], v[104:105], v[132:133] op_sel:[0,1] op_sel_hi:[1,1]
	v_pk_mul_f32 v[98:99], v[98:99], v[132:133] op_sel:[0,1] op_sel_hi:[1,1]
	v_pk_mul_f32 v[100:101], v[100:101], v[132:133] op_sel:[0,1] op_sel_hi:[1,1]
	v_mul_f32_e32 v184, v102, v102
	v_fmac_f32_e32 v184, v103, v103
	v_fmac_f32_e32 v184, v104, v104
	v_fmac_f32_e32 v184, v105, v105
	v_fmac_f32_e32 v184, v98, v98
	v_fmac_f32_e32 v184, v99, v99
	v_fmac_f32_e32 v184, v100, v100
	v_fmac_f32_e32 v184, v101, v101
	v_pk_mul_f32 v[38:39], v[38:39], v[132:133] op_sel:[0,1] op_sel_hi:[1,1]
	v_pk_mul_f32 v[40:41], v[40:41], v[132:133] op_sel:[0,1] op_sel_hi:[1,1]
	v_pk_mul_f32 v[34:35], v[34:35], v[132:133] op_sel:[0,1] op_sel_hi:[1,1]
	v_pk_mul_f32 v[36:37], v[36:37], v[132:133] op_sel:[0,1] op_sel_hi:[1,1]
	v_mul_f32_e32 v185, v38, v38
	v_fmac_f32_e32 v185, v39, v39
	v_fmac_f32_e32 v185, v40, v40
	v_fmac_f32_e32 v185, v41, v41
	v_fmac_f32_e32 v185, v34, v34
	v_fmac_f32_e32 v185, v35, v35
	v_fmac_f32_e32 v185, v36, v36
	v_fmac_f32_e32 v185, v37, v37
	v_pk_mul_f32 v[94:95], v[94:95], v[134:135] op_sel_hi:[1,0]
	v_pk_mul_f32 v[96:97], v[96:97], v[134:135] op_sel_hi:[1,0]
; __device__ __forceinline__ void unpack8(const u32x4 w, f32x4& a, f32x4& b) { a[0] = bf_lo(w.x); a[1] = bf_hi(w.x); a[2] = bf_lo(w.y); a[3] = bf_hi(w.y); b[0] = bf_lo(w.z); b[1] = bf_hi(w.z); b[2] = bf_lo(w.w); b[3] = bf_hi(w.w); }
; __device__ void ph_qknorm(bf16_t* Z, const float* qg, const float* kg, const int WID) {
;     ...
;             f32x4 a0, a1, a2, a3; unpack8(w0[q], a0, a1); unpack8(w1[q], a2, a3);
;             float ss = 0.f;
; #pragma unroll
;             for (int j = 0; j < 4; ++j) ss += a0[j] * a0[j] + a1[j] * a1[j] + a2[j] * a2[j] + a3[j] * a3[j];
;             ss += __shfl_xor(ss, 1); ss += __shfl_xor(ss, 2); ss += __shfl_xor(ss, 4);
	v_pk_mul_f32 v[90:91], v[90:91], v[134:135] op_sel_hi:[1,0]
	v_pk_mul_f32 v[92:93], v[92:93], v[134:135] op_sel_hi:[1,0]
	v_mul_f32_e32 v186, v94, v94
	v_fmac_f32_e32 v186, v95, v95
	v_fmac_f32_e32 v186, v96, v96
	v_fmac_f32_e32 v186, v97, v97
	v_fmac_f32_e32 v186, v90, v90
	v_fmac_f32_e32 v186, v91, v91
	v_fmac_f32_e32 v186, v92, v92
	v_fmac_f32_e32 v186, v93, v93
	v_pk_mul_f32 v[30:31], v[30:31], v[134:135] op_sel_hi:[1,0]
	v_pk_mul_f32 v[32:33], v[32:33], v[134:135] op_sel_hi:[1,0]
	v_pk_mul_f32 v[26:27], v[26:27], v[134:135] op_sel_hi:[1,0]
	v_pk_mul_f32 v[28:29], v[28:29], v[134:135] op_sel_hi:[1,0]
	v_mul_f32_e32 v187, v30, v30
	v_fmac_f32_e32 v187, v31, v31
	v_fmac_f32_e32 v187, v32, v32
	v_fmac_f32_e32 v187, v33, v33
	v_fmac_f32_e32 v187, v26, v26
	v_fmac_f32_e32 v187, v27, v27
	v_fmac_f32_e32 v187, v28, v28
	v_fmac_f32_e32 v187, v29, v29
	v_pk_mul_f32 v[86:87], v[86:87], v[134:135] op_sel:[0,1] op_sel_hi:[1,1]
	v_pk_mul_f32 v[88:89], v[88:89], v[134:135] op_sel:[0,1] op_sel_hi:[1,1]
	v_pk_mul_f32 v[82:83], v[82:83], v[134:135] op_sel:[0,1] op_sel_hi:[1,1]
	v_pk_mul_f32 v[84:85], v[84:85], v[134:135] op_sel:[0,1] op_sel_hi:[1,1]
	v_mul_f32_e32 v188, v86, v86
	v_fmac_f32_e32 v188, v87, v87
	v_fmac_f32_e32 v188, v88, v88
	v_fmac_f32_e32 v188, v89, v89
	v_fmac_f32_e32 v188, v82, v82
	v_fmac_f32_e32 v188, v83, v83
	v_fmac_f32_e32 v188, v84, v84
	v_fmac_f32_e32 v188, v85, v85
	v_pk_mul_f32 v[22:23], v[22:23], v[134:135] op_sel:[0,1] op_sel_hi:[1,1]
	v_pk_mul_f32 v[24:25], v[24:25], v[134:135] op_sel:[0,1] op_sel_hi:[1,1]
	v_pk_mul_f32 v[18:19], v[18:19], v[134:135] op_sel:[0,1] op_sel_hi:[1,1]
	v_pk_mul_f32 v[20:21], v[20:21], v[134:135] op_sel:[0,1] op_sel_hi:[1,1]
	v_mul_f32_e32 v189, v22, v22
	v_fmac_f32_e32 v189, v23, v23
	v_fmac_f32_e32 v189, v24, v24
	v_fmac_f32_e32 v189, v25, v25
	v_fmac_f32_e32 v189, v18, v18
	v_fmac_f32_e32 v189, v19, v19
	v_fmac_f32_e32 v189, v20, v20
	v_fmac_f32_e32 v189, v21, v21
	v_pk_mul_f32 v[78:79], v[78:79], v[136:137] op_sel_hi:[1,0]
	v_pk_mul_f32 v[80:81], v[80:81], v[136:137] op_sel_hi:[1,0]
	v_pk_mul_f32 v[74:75], v[74:75], v[136:137] op_sel_hi:[1,0]
	v_pk_mul_f32 v[76:77], v[76:77], v[136:137] op_sel_hi:[1,0]
	v_mul_f32_e32 v190, v78, v78
	v_fmac_f32_e32 v190, v79, v79
	v_fmac_f32_e32 v190, v80, v80
	v_fmac_f32_e32 v190, v81, v81
	v_fmac_f32_e32 v190, v74, v74
	v_fmac_f32_e32 v190, v75, v75
	v_fmac_f32_e32 v190, v76, v76
	v_fmac_f32_e32 v190, v77, v77
	v_pk_mul_f32 v[14:15], v[14:15], v[136:137] op_sel_hi:[1,0]
	v_pk_mul_f32 v[16:17], v[16:17], v[136:137] op_sel_hi:[1,0]
	v_pk_mul_f32 v[10:11], v[10:11], v[136:137] op_sel_hi:[1,0]
	v_pk_mul_f32 v[12:13], v[12:13], v[136:137] op_sel_hi:[1,0]
	v_mul_f32_e32 v191, v14, v14
	v_fmac_f32_e32 v191, v15, v15
	v_fmac_f32_e32 v191, v16, v16
	v_fmac_f32_e32 v191, v17, v17
	v_fmac_f32_e32 v191, v10, v10
	v_fmac_f32_e32 v191, v11, v11
	v_fmac_f32_e32 v191, v12, v12
	v_fmac_f32_e32 v191, v13, v13
	v_pk_mul_f32 v[70:71], v[70:71], v[136:137] op_sel:[0,1] op_sel_hi:[1,1]
	v_pk_mul_f32 v[72:73], v[72:73], v[136:137] op_sel:[0,1] op_sel_hi:[1,1]
	v_pk_mul_f32 v[66:67], v[66:67], v[136:137] op_sel:[0,1] op_sel_hi:[1,1]
	v_pk_mul_f32 v[68:69], v[68:69], v[136:137] op_sel:[0,1] op_sel_hi:[1,1]
	v_mul_f32_e32 v192, v70, v70
	v_fmac_f32_e32 v192, v71, v71
	v_fmac_f32_e32 v192, v72, v72
	v_fmac_f32_e32 v192, v73, v73
	v_fmac_f32_e32 v192, v66, v66
	v_fmac_f32_e32 v192, v67, v67
	v_fmac_f32_e32 v192, v68, v68
	v_fmac_f32_e32 v192, v69, v69
	v_pk_mul_f32 v[6:7], v[6:7], v[136:137] op_sel:[0,1] op_sel_hi:[1,1]
	v_pk_mul_f32 v[8:9], v[8:9], v[136:137] op_sel:[0,1] op_sel_hi:[1,1]
	v_pk_mul_f32 v[2:3], v[2:3], v[136:137] op_sel:[0,1] op_sel_hi:[1,1]
	v_pk_mul_f32 v[4:5], v[4:5], v[136:137] op_sel:[0,1] op_sel_hi:[1,1]
	v_mul_f32_e32 v193, v6, v6
	v_fmac_f32_e32 v193, v7, v7
	v_fmac_f32_e32 v193, v8, v8
	v_fmac_f32_e32 v193, v9, v9
	v_fmac_f32_e32 v193, v2, v2
	v_fmac_f32_e32 v193, v3, v3
	v_fmac_f32_e32 v193, v4, v4
	v_fmac_f32_e32 v193, v5, v5
	ds_bpermute_b32 v194, v164, v178
	ds_bpermute_b32 v195, v164, v179
	ds_bpermute_b32 v196, v164, v180
	ds_bpermute_b32 v197, v164, v181
	ds_bpermute_b32 v198, v164, v182
	ds_bpermute_b32 v199, v164, v183
	ds_bpermute_b32 v200, v164, v184
	ds_bpermute_b32 v201, v164, v185
	s_waitcnt lgkmcnt(0)
	v_add_f32_e32 v178, v178, v194
	v_add_f32_e32 v179, v179, v195
	v_add_f32_e32 v180, v180, v196
	v_add_f32_e32 v181, v181, v197
	v_add_f32_e32 v182, v182, v198
	v_add_f32_e32 v183, v183, v199
	v_add_f32_e32 v184, v184, v200
	v_add_f32_e32 v185, v185, v201
	ds_bpermute_b32 v202, v164, v186
	ds_bpermute_b32 v203, v164, v187
	ds_bpermute_b32 v204, v164, v188
	ds_bpermute_b32 v205, v164, v189
	ds_bpermute_b32 v206, v164, v190
	ds_bpermute_b32 v207, v164, v191
	ds_bpermute_b32 v208, v164, v192
	ds_bpermute_b32 v209, v164, v193
	s_waitcnt lgkmcnt(0)
	v_add_f32_e32 v186, v186, v202
	v_add_f32_e32 v187, v187, v203
	v_add_f32_e32 v188, v188, v204
	v_add_f32_e32 v189, v189, v205
	v_add_f32_e32 v190, v190, v206
	v_add_f32_e32 v191, v191, v207
	v_add_f32_e32 v192, v192, v208
	v_add_f32_e32 v193, v193, v209
	ds_bpermute_b32 v194, v165, v178
	ds_bpermute_b32 v195, v165, v179
	ds_bpermute_b32 v196, v165, v180
	ds_bpermute_b32 v197, v165, v181
	ds_bpermute_b32 v198, v165, v182
	ds_bpermute_b32 v199, v165, v183
	ds_bpermute_b32 v200, v165, v184
	ds_bpermute_b32 v201, v165, v185
	s_waitcnt lgkmcnt(0)
	v_add_f32_e32 v178, v178, v194
	v_add_f32_e32 v179, v179, v195
	v_add_f32_e32 v180, v180, v196
	v_add_f32_e32 v181, v181, v197
	v_add_f32_e32 v182, v182, v198
	v_add_f32_e32 v183, v183, v199
	v_add_f32_e32 v184, v184, v200
	v_add_f32_e32 v185, v185, v201
	ds_bpermute_b32 v202, v165, v186
	ds_bpermute_b32 v203, v165, v187
	ds_bpermute_b32 v204, v165, v188
	ds_bpermute_b32 v205, v165, v189
	ds_bpermute_b32 v206, v165, v190
	ds_bpermute_b32 v207, v165, v191
	ds_bpermute_b32 v208, v165, v192
	ds_bpermute_b32 v209, v165, v193
	s_waitcnt lgkmcnt(0)
	v_add_f32_e32 v186, v186, v202
	v_add_f32_e32 v187, v187, v203
	v_add_f32_e32 v188, v188, v204
	v_add_f32_e32 v189, v189, v205
	v_add_f32_e32 v190, v190, v206
	v_add_f32_e32 v191, v191, v207
	v_add_f32_e32 v192, v192, v208
	v_add_f32_e32 v193, v193, v209
	ds_write_b32 v166, v178 offset:0
	ds_write_b32 v166, v179 offset:16
	ds_write_b32 v166, v180 offset:512
	ds_write_b32 v166, v181 offset:528
	ds_write_b32 v166, v182 offset:1024
	ds_write_b32 v166, v183 offset:1040
	ds_write_b32 v166, v184 offset:1536
	ds_write_b32 v166, v185 offset:1552
	s_waitcnt lgkmcnt(0)
	ds_write_b32 v166, v186 offset:4096
	ds_write_b32 v166, v187 offset:4112
	ds_write_b32 v166, v188 offset:4608
	ds_write_b32 v166, v189 offset:4624
	ds_write_b32 v166, v190 offset:5120
	ds_write_b32 v166, v191 offset:5136
	ds_write_b32 v166, v192 offset:5632
	ds_write_b32 v166, v193 offset:5648
	s_waitcnt lgkmcnt(0)
	s_barrier
; __device__ __forceinline__ u32x4 pack8(const f32x4 a, const f32x4 b) { u32x4 w; w.x = cvt_pk_bf16(a[0], a[1]); w.y = cvt_pk_bf16(a[2], a[3]); w.z = cvt_pk_bf16(b[0], b[1]); w.w = cvt_pk_bf16(b[2], b[3]); return w; }
; __device__ void ph_qknorm(bf16_t* Z, const float* qg, const float* kg, const int WID) {
;     ...
;             ss += __shfl_xor(ss, 1); ss += __shfl_xor(ss, 2); ss += __shfl_xor(ss, 4);
;             const float rstd = rsqrtf(ss * (1.0f / 128.0f) + EPS) * (isk ? 1.0f : 0.08838834764831845f);
;             const f32x4 g0 = isk ? kgv[0] : qgv[0], g1 = isk ? kgv[1] : qgv[1], g2 = isk ? kgv[2] : qgv[2], g3 = isk ? kgv[3] : qgv[3];
;             *(u32x4*)ptr = pack8(a0 * rstd * g0, a1 * rstd * g1); *(u32x4*)(ptr + 8) = pack8(a2 * rstd * g2, a3 * rstd * g3);
	ds_read_b128 v[194:197], v167 offset:0
	ds_read_b128 v[198:201], v167 offset:16
	ds_read_b128 v[202:205], v167 offset:512
	ds_read_b128 v[206:209], v167 offset:528
	s_waitcnt lgkmcnt(0)
	v_add_f32_e32 v194, v194, v195
	v_add_f32_e32 v196, v196, v197
	v_add_f32_e32 v178, v194, v196
	v_add_f32_e32 v198, v198, v199
	v_add_f32_e32 v200, v200, v201
	v_add_f32_e32 v179, v198, v200
	v_add_f32_e32 v202, v202, v203
	v_add_f32_e32 v204, v204, v205
	v_add_f32_e32 v180, v202, v204
	v_add_f32_e32 v206, v206, v207
	v_add_f32_e32 v208, v208, v209
	v_add_f32_e32 v181, v206, v208
	ds_read_b128 v[194:197], v167 offset:1024
	ds_read_b128 v[198:201], v167 offset:1040
	ds_read_b128 v[202:205], v167 offset:1536
	ds_read_b128 v[206:209], v167 offset:1552
	s_waitcnt lgkmcnt(0)
	v_add_f32_e32 v194, v194, v195
	v_add_f32_e32 v196, v196, v197
	v_add_f32_e32 v182, v194, v196
	v_add_f32_e32 v198, v198, v199
	v_add_f32_e32 v200, v200, v201
	v_add_f32_e32 v183, v198, v200
	v_add_f32_e32 v202, v202, v203
	v_add_f32_e32 v204, v204, v205
	v_add_f32_e32 v184, v202, v204
	v_add_f32_e32 v206, v206, v207
	v_add_f32_e32 v208, v208, v209
	v_add_f32_e32 v185, v206, v208
	ds_read_b128 v[194:197], v167 offset:4096
	ds_read_b128 v[198:201], v167 offset:4112
	ds_read_b128 v[202:205], v167 offset:4608
	ds_read_b128 v[206:209], v167 offset:4624
	s_waitcnt lgkmcnt(0)
	v_add_f32_e32 v194, v194, v195
	v_add_f32_e32 v196, v196, v197
	v_add_f32_e32 v186, v194, v196
	v_add_f32_e32 v198, v198, v199
	v_add_f32_e32 v200, v200, v201
	v_add_f32_e32 v187, v198, v200
	v_add_f32_e32 v202, v202, v203
	v_add_f32_e32 v204, v204, v205
	v_add_f32_e32 v188, v202, v204
	v_add_f32_e32 v206, v206, v207
	v_add_f32_e32 v208, v208, v209
	v_add_f32_e32 v189, v206, v208
	ds_read_b128 v[194:197], v167 offset:5120
	ds_read_b128 v[198:201], v167 offset:5136
	ds_read_b128 v[202:205], v167 offset:5632
	ds_read_b128 v[206:209], v167 offset:5648
	s_waitcnt lgkmcnt(0)
	v_add_f32_e32 v194, v194, v195
	v_add_f32_e32 v196, v196, v197
	v_add_f32_e32 v190, v194, v196
	v_add_f32_e32 v198, v198, v199
	v_add_f32_e32 v200, v200, v201
	v_add_f32_e32 v191, v198, v200
	v_add_f32_e32 v202, v202, v203
	v_add_f32_e32 v204, v204, v205
	v_add_f32_e32 v192, v202, v204
	v_add_f32_e32 v206, v206, v207
	v_add_f32_e32 v208, v208, v209
	v_add_f32_e32 v193, v206, v208
	v_fmamk_f32 v178, v178, 0x3c000000, v251
	v_fmamk_f32 v179, v179, 0x3c000000, v251
	v_fmamk_f32 v180, v180, 0x3c000000, v251
	v_fmamk_f32 v181, v181, 0x3c000000, v251
	v_fmamk_f32 v182, v182, 0x3c000000, v251
	v_fmamk_f32 v183, v183, 0x3c000000, v251
	v_fmamk_f32 v184, v184, 0x3c000000, v251
	v_fmamk_f32 v185, v185, 0x3c000000, v251
	v_fmamk_f32 v186, v186, 0x3c000000, v251
	v_fmamk_f32 v187, v187, 0x3c000000, v251
	v_fmamk_f32 v188, v188, 0x3c000000, v251
	v_fmamk_f32 v189, v189, 0x3c000000, v251
	v_fmamk_f32 v190, v190, 0x3c000000, v251
	v_fmamk_f32 v191, v191, 0x3c000000, v251
	v_fmamk_f32 v192, v192, 0x3c000000, v251
	v_fmamk_f32 v193, v193, 0x3c000000, v251
	v_rsq_f32_e32 v178, v178
	v_rsq_f32_e32 v179, v179
	v_rsq_f32_e32 v180, v180
	v_rsq_f32_e32 v181, v181
	v_rsq_f32_e32 v182, v182
	v_rsq_f32_e32 v183, v183
	v_rsq_f32_e32 v184, v184
	v_rsq_f32_e32 v185, v185
	v_rsq_f32_e32 v186, v186
	v_rsq_f32_e32 v187, v187
	v_rsq_f32_e32 v188, v188
	v_rsq_f32_e32 v189, v189
	v_rsq_f32_e32 v190, v190
	v_rsq_f32_e32 v191, v191
	v_rsq_f32_e32 v192, v192
	v_rsq_f32_e32 v193, v193
	s_waitcnt vmcnt(0)
	v_mul_f32_e32 v178, s11, v178
	v_mul_f32_e32 v179, s11, v179
	v_mul_f32_e32 v180, s11, v180
	v_mul_f32_e32 v181, s11, v181
	v_mul_f32_e32 v182, s11, v182
	v_mul_f32_e32 v183, s11, v183
	v_mul_f32_e32 v184, s11, v184
	v_mul_f32_e32 v185, s11, v185
	v_mul_f32_e32 v186, s11, v186
	v_mul_f32_e32 v187, s11, v187
	v_mul_f32_e32 v188, s11, v188
	v_mul_f32_e32 v189, s11, v189
	v_mul_f32_e32 v190, s11, v190
	v_mul_f32_e32 v191, s11, v191
	v_mul_f32_e32 v192, s11, v192
	v_mul_f32_e32 v193, s11, v193
	v_mov_b32_e32 v168, v163
	v_pk_mul_f32 v[126:127], v[126:127], v[178:179] op_sel_hi:[1,0]
	v_pk_mul_f32 v[128:129], v[128:129], v[178:179] op_sel_hi:[1,0]
	v_pk_mul_f32 v[122:123], v[122:123], v[178:179] op_sel_hi:[1,0]
	v_pk_mul_f32 v[124:125], v[124:125], v[178:179] op_sel_hi:[1,0]
	v_pk_mul_f32 v[126:127], v[126:127], v[138:139]
	v_pk_mul_f32 v[128:129], v[128:129], v[140:141]
	v_pk_mul_f32 v[122:123], v[122:123], v[142:143]
	v_pk_mul_f32 v[124:125], v[124:125], v[144:145]
	v_cvt_pk_bf16_f32 v126, v126, v127
	v_cvt_pk_bf16_f32 v127, v128, v129
	v_cvt_pk_bf16_f32 v128, v122, v123
	v_cvt_pk_bf16_f32 v129, v124, v125
	global_store_dwordx4 v168, v[126:129], s[30:31]
	v_pk_mul_f32 v[62:63], v[62:63], v[178:179] op_sel:[0,1] op_sel_hi:[1,1]
	v_pk_mul_f32 v[64:65], v[64:65], v[178:179] op_sel:[0,1] op_sel_hi:[1,1]
	v_pk_mul_f32 v[58:59], v[58:59], v[178:179] op_sel:[0,1] op_sel_hi:[1,1]
	v_pk_mul_f32 v[60:61], v[60:61], v[178:179] op_sel:[0,1] op_sel_hi:[1,1]
	v_pk_mul_f32 v[62:63], v[62:63], v[138:139]
	v_pk_mul_f32 v[64:65], v[64:65], v[140:141]
	v_pk_mul_f32 v[58:59], v[58:59], v[142:143]
	v_pk_mul_f32 v[60:61], v[60:61], v[144:145]
	v_cvt_pk_bf16_f32 v62, v62, v63
	v_cvt_pk_bf16_f32 v63, v64, v65
	v_cvt_pk_bf16_f32 v64, v58, v59
	v_cvt_pk_bf16_f32 v65, v60, v61
	global_store_dwordx4 v168, v[62:65], s[30:31] offset:256
	v_add_u32_e32 v168, 0x48000, v163
	v_pk_mul_f32 v[118:119], v[118:119], v[180:181] op_sel_hi:[1,0]
	v_pk_mul_f32 v[120:121], v[120:121], v[180:181] op_sel_hi:[1,0]
	v_pk_mul_f32 v[114:115], v[114:115], v[180:181] op_sel_hi:[1,0]
	v_pk_mul_f32 v[116:117], v[116:117], v[180:181] op_sel_hi:[1,0]
	v_pk_mul_f32 v[118:119], v[118:119], v[138:139]
	v_pk_mul_f32 v[120:121], v[120:121], v[140:141]
; __device__ __forceinline__ u32x4 pack8(const f32x4 a, const f32x4 b) { u32x4 w; w.x = cvt_pk_bf16(a[0], a[1]); w.y = cvt_pk_bf16(a[2], a[3]); w.z = cvt_pk_bf16(b[0], b[1]); w.w = cvt_pk_bf16(b[2], b[3]); return w; }
; __device__ void ph_qknorm(bf16_t* Z, const float* qg, const float* kg, const int WID) {
;     ...
;             const float rstd = rsqrtf(ss * (1.0f / 128.0f) + EPS) * (isk ? 1.0f : 0.08838834764831845f);
;             const f32x4 g0 = isk ? kgv[0] : qgv[0], g1 = isk ? kgv[1] : qgv[1], g2 = isk ? kgv[2] : qgv[2], g3 = isk ? kgv[3] : qgv[3];
;             *(u32x4*)ptr = pack8(a0 * rstd * g0, a1 * rstd * g1); *(u32x4*)(ptr + 8) = pack8(a2 * rstd * g2, a3 * rstd * g3);
	v_pk_mul_f32 v[114:115], v[114:115], v[142:143]
	v_pk_mul_f32 v[116:117], v[116:117], v[144:145]
	v_cvt_pk_bf16_f32 v118, v118, v119
	v_cvt_pk_bf16_f32 v119, v120, v121
	v_cvt_pk_bf16_f32 v120, v114, v115
	v_cvt_pk_bf16_f32 v121, v116, v117
	global_store_dwordx4 v168, v[118:121], s[30:31]
	v_pk_mul_f32 v[54:55], v[54:55], v[180:181] op_sel:[0,1] op_sel_hi:[1,1]
	v_pk_mul_f32 v[56:57], v[56:57], v[180:181] op_sel:[0,1] op_sel_hi:[1,1]
	v_pk_mul_f32 v[50:51], v[50:51], v[180:181] op_sel:[0,1] op_sel_hi:[1,1]
	v_pk_mul_f32 v[52:53], v[52:53], v[180:181] op_sel:[0,1] op_sel_hi:[1,1]
	v_pk_mul_f32 v[54:55], v[54:55], v[138:139]
	v_pk_mul_f32 v[56:57], v[56:57], v[140:141]
	v_pk_mul_f32 v[50:51], v[50:51], v[142:143]
	v_pk_mul_f32 v[52:53], v[52:53], v[144:145]
	v_cvt_pk_bf16_f32 v54, v54, v55
	v_cvt_pk_bf16_f32 v55, v56, v57
	v_cvt_pk_bf16_f32 v56, v50, v51
	v_cvt_pk_bf16_f32 v57, v52, v53
	global_store_dwordx4 v168, v[54:57], s[30:31] offset:256
	v_add_u32_e32 v168, 0x90000, v163
	v_pk_mul_f32 v[110:111], v[110:111], v[182:183] op_sel_hi:[1,0]
	v_pk_mul_f32 v[112:113], v[112:113], v[182:183] op_sel_hi:[1,0]
	v_pk_mul_f32 v[106:107], v[106:107], v[182:183] op_sel_hi:[1,0]
	v_pk_mul_f32 v[108:109], v[108:109], v[182:183] op_sel_hi:[1,0]
	v_pk_mul_f32 v[110:111], v[110:111], v[138:139]
	v_pk_mul_f32 v[112:113], v[112:113], v[140:141]
	v_pk_mul_f32 v[106:107], v[106:107], v[142:143]
	v_pk_mul_f32 v[108:109], v[108:109], v[144:145]
	v_cvt_pk_bf16_f32 v110, v110, v111
	v_cvt_pk_bf16_f32 v111, v112, v113
	v_cvt_pk_bf16_f32 v112, v106, v107
	v_cvt_pk_bf16_f32 v113, v108, v109
	global_store_dwordx4 v168, v[110:113], s[30:31]
	v_pk_mul_f32 v[46:47], v[46:47], v[182:183] op_sel:[0,1] op_sel_hi:[1,1]
	v_pk_mul_f32 v[48:49], v[48:49], v[182:183] op_sel:[0,1] op_sel_hi:[1,1]
	v_pk_mul_f32 v[42:43], v[42:43], v[182:183] op_sel:[0,1] op_sel_hi:[1,1]
	v_pk_mul_f32 v[44:45], v[44:45], v[182:183] op_sel:[0,1] op_sel_hi:[1,1]
	v_pk_mul_f32 v[46:47], v[46:47], v[138:139]
	v_pk_mul_f32 v[48:49], v[48:49], v[140:141]
	v_pk_mul_f32 v[42:43], v[42:43], v[142:143]
	v_pk_mul_f32 v[44:45], v[44:45], v[144:145]
	v_cvt_pk_bf16_f32 v46, v46, v47
	v_cvt_pk_bf16_f32 v47, v48, v49
	v_cvt_pk_bf16_f32 v48, v42, v43
	v_cvt_pk_bf16_f32 v49, v44, v45
	global_store_dwordx4 v168, v[46:49], s[30:31] offset:256
	v_add_u32_e32 v168, 0xd8000, v163
	v_pk_mul_f32 v[102:103], v[102:103], v[184:185] op_sel_hi:[1,0]
	v_pk_mul_f32 v[104:105], v[104:105], v[184:185] op_sel_hi:[1,0]
	v_pk_mul_f32 v[98:99], v[98:99], v[184:185] op_sel_hi:[1,0]
	v_pk_mul_f32 v[100:101], v[100:101], v[184:185] op_sel_hi:[1,0]
	v_pk_mul_f32 v[102:103], v[102:103], v[138:139]
	v_pk_mul_f32 v[104:105], v[104:105], v[140:141]
	v_pk_mul_f32 v[98:99], v[98:99], v[142:143]
	v_pk_mul_f32 v[100:101], v[100:101], v[144:145]
	v_cvt_pk_bf16_f32 v102, v102, v103
	v_cvt_pk_bf16_f32 v103, v104, v105
	v_cvt_pk_bf16_f32 v104, v98, v99
	v_cvt_pk_bf16_f32 v105, v100, v101
	global_store_dwordx4 v168, v[102:105], s[30:31]
	v_pk_mul_f32 v[38:39], v[38:39], v[184:185] op_sel:[0,1] op_sel_hi:[1,1]
	v_pk_mul_f32 v[40:41], v[40:41], v[184:185] op_sel:[0,1] op_sel_hi:[1,1]
	v_pk_mul_f32 v[34:35], v[34:35], v[184:185] op_sel:[0,1] op_sel_hi:[1,1]
	v_pk_mul_f32 v[36:37], v[36:37], v[184:185] op_sel:[0,1] op_sel_hi:[1,1]
	v_pk_mul_f32 v[38:39], v[38:39], v[138:139]
	v_pk_mul_f32 v[40:41], v[40:41], v[140:141]
	v_pk_mul_f32 v[34:35], v[34:35], v[142:143]
	v_pk_mul_f32 v[36:37], v[36:37], v[144:145]
	v_cvt_pk_bf16_f32 v38, v38, v39
	v_cvt_pk_bf16_f32 v39, v40, v41
	v_cvt_pk_bf16_f32 v40, v34, v35
	v_cvt_pk_bf16_f32 v41, v36, v37
	global_store_dwordx4 v168, v[38:41], s[30:31] offset:256
	v_add_u32_e32 v168, 0x240000, v163
	v_pk_mul_f32 v[94:95], v[94:95], v[186:187] op_sel_hi:[1,0]
	v_pk_mul_f32 v[96:97], v[96:97], v[186:187] op_sel_hi:[1,0]
	v_pk_mul_f32 v[90:91], v[90:91], v[186:187] op_sel_hi:[1,0]
	v_pk_mul_f32 v[92:93], v[92:93], v[186:187] op_sel_hi:[1,0]
	v_pk_mul_f32 v[94:95], v[94:95], v[138:139]
	v_pk_mul_f32 v[96:97], v[96:97], v[140:141]
	v_pk_mul_f32 v[90:91], v[90:91], v[142:143]
	v_pk_mul_f32 v[92:93], v[92:93], v[144:145]
	v_cvt_pk_bf16_f32 v94, v94, v95
	v_cvt_pk_bf16_f32 v95, v96, v97
	v_cvt_pk_bf16_f32 v96, v90, v91
	v_cvt_pk_bf16_f32 v97, v92, v93
	global_store_dwordx4 v168, v[94:97], s[30:31]
	v_pk_mul_f32 v[30:31], v[30:31], v[186:187] op_sel:[0,1] op_sel_hi:[1,1]
	v_pk_mul_f32 v[32:33], v[32:33], v[186:187] op_sel:[0,1] op_sel_hi:[1,1]
; __device__ __forceinline__ float rstd_of(float ss) { return rsqrtf(ss * (1.0f / DM) + EPS); }
; __device__ __forceinline__ float sigmoidf_(float x) { return __builtin_amdgcn_rcpf(1.0f + __expf(-x)); }
; __device__ __forceinline__ u32x4 pack8(const f32x4 a, const f32x4 b) { u32x4 w; w.x = cvt_pk_bf16(a[0], a[1]); w.y = cvt_pk_bf16(a[2], a[3]); w.z = cvt_pk_bf16(b[0], b[1]); w.w = cvt_pk_bf16(b[2], b[3]); return w; }
;     __device__ __forceinline__ void operator()(const AccT& acc, const Unit& u, int wr, int wc, int fr, int fq) const {
;     ...
;                         const float rs = rstd_of(rsv[ai][m]);
;                         f32x4 v0 = acc[ai][bj][m][0] * rs, v1 = acc[ai][bj][m][1] * rs;
;                         if (gate) {
; #pragma unroll
;                             for (int j = 0; j < 4; ++j) { v0[j] = sigmoidf_(v0[j] + b0[j]); v1[j] = sigmoidf_(v1[j] + b1[j]); } }
;                         *(u32x4*)(Z + (size_t)(row0 + ai * 128 + m * 16) * ZW + col0 + bj * 128) = pack8(v0, v1);
; __device__ void ph_qknorm(bf16_t* Z, const float* qg, const float* kg, const int WID) {
;     ...
;             const float rstd = rsqrtf(ss * (1.0f / 128.0f) + EPS) * (isk ? 1.0f : 0.08838834764831845f);
;             const f32x4 g0 = isk ? kgv[0] : qgv[0], g1 = isk ? kgv[1] : qgv[1], g2 = isk ? kgv[2] : qgv[2], g3 = isk ? kgv[3] : qgv[3];
;             *(u32x4*)ptr = pack8(a0 * rstd * g0, a1 * rstd * g1); *(u32x4*)(ptr + 8) = pack8(a2 * rstd * g2, a3 * rstd * g3);
	v_pk_mul_f32 v[26:27], v[26:27], v[186:187] op_sel:[0,1] op_sel_hi:[1,1]
	v_pk_mul_f32 v[28:29], v[28:29], v[186:187] op_sel:[0,1] op_sel_hi:[1,1]
	v_pk_mul_f32 v[30:31], v[30:31], v[138:139]
	v_pk_mul_f32 v[32:33], v[32:33], v[140:141]
	v_pk_mul_f32 v[26:27], v[26:27], v[142:143]
	v_pk_mul_f32 v[28:29], v[28:29], v[144:145]
	v_cvt_pk_bf16_f32 v30, v30, v31
	v_cvt_pk_bf16_f32 v31, v32, v33
	v_cvt_pk_bf16_f32 v32, v26, v27
	v_cvt_pk_bf16_f32 v33, v28, v29
	global_store_dwordx4 v168, v[30:33], s[30:31] offset:256
	v_add_u32_e32 v168, 0x288000, v163
	v_pk_mul_f32 v[86:87], v[86:87], v[188:189] op_sel_hi:[1,0]
	v_pk_mul_f32 v[88:89], v[88:89], v[188:189] op_sel_hi:[1,0]
	v_pk_mul_f32 v[82:83], v[82:83], v[188:189] op_sel_hi:[1,0]
	v_pk_mul_f32 v[84:85], v[84:85], v[188:189] op_sel_hi:[1,0]
	v_pk_mul_f32 v[86:87], v[86:87], v[138:139]
	v_pk_mul_f32 v[88:89], v[88:89], v[140:141]
	v_pk_mul_f32 v[82:83], v[82:83], v[142:143]
	v_pk_mul_f32 v[84:85], v[84:85], v[144:145]
	v_cvt_pk_bf16_f32 v86, v86, v87
	v_cvt_pk_bf16_f32 v87, v88, v89
	v_cvt_pk_bf16_f32 v88, v82, v83
	v_cvt_pk_bf16_f32 v89, v84, v85
	global_store_dwordx4 v168, v[86:89], s[30:31]
	v_pk_mul_f32 v[22:23], v[22:23], v[188:189] op_sel:[0,1] op_sel_hi:[1,1]
	v_pk_mul_f32 v[24:25], v[24:25], v[188:189] op_sel:[0,1] op_sel_hi:[1,1]
	v_pk_mul_f32 v[18:19], v[18:19], v[188:189] op_sel:[0,1] op_sel_hi:[1,1]
	v_pk_mul_f32 v[20:21], v[20:21], v[188:189] op_sel:[0,1] op_sel_hi:[1,1]
	v_pk_mul_f32 v[22:23], v[22:23], v[138:139]
	v_pk_mul_f32 v[24:25], v[24:25], v[140:141]
	v_pk_mul_f32 v[18:19], v[18:19], v[142:143]
	v_pk_mul_f32 v[20:21], v[20:21], v[144:145]
	v_cvt_pk_bf16_f32 v22, v22, v23
	v_cvt_pk_bf16_f32 v23, v24, v25
	v_cvt_pk_bf16_f32 v24, v18, v19
	v_cvt_pk_bf16_f32 v25, v20, v21
	global_store_dwordx4 v168, v[22:25], s[30:31] offset:256
	v_add_u32_e32 v168, 0x2d0000, v163
	v_pk_mul_f32 v[78:79], v[78:79], v[190:191] op_sel_hi:[1,0]
	v_pk_mul_f32 v[80:81], v[80:81], v[190:191] op_sel_hi:[1,0]
	v_pk_mul_f32 v[74:75], v[74:75], v[190:191] op_sel_hi:[1,0]
	v_pk_mul_f32 v[76:77], v[76:77], v[190:191] op_sel_hi:[1,0]
	v_pk_mul_f32 v[78:79], v[78:79], v[138:139]
	v_pk_mul_f32 v[80:81], v[80:81], v[140:141]
	v_pk_mul_f32 v[74:75], v[74:75], v[142:143]
	v_pk_mul_f32 v[76:77], v[76:77], v[144:145]
	v_cvt_pk_bf16_f32 v78, v78, v79
	v_cvt_pk_bf16_f32 v79, v80, v81
	v_cvt_pk_bf16_f32 v80, v74, v75
	v_cvt_pk_bf16_f32 v81, v76, v77
	global_store_dwordx4 v168, v[78:81], s[30:31]
	v_pk_mul_f32 v[14:15], v[14:15], v[190:191] op_sel:[0,1] op_sel_hi:[1,1]
	v_pk_mul_f32 v[16:17], v[16:17], v[190:191] op_sel:[0,1] op_sel_hi:[1,1]
	v_pk_mul_f32 v[10:11], v[10:11], v[190:191] op_sel:[0,1] op_sel_hi:[1,1]
	v_pk_mul_f32 v[12:13], v[12:13], v[190:191] op_sel:[0,1] op_sel_hi:[1,1]
	v_pk_mul_f32 v[14:15], v[14:15], v[138:139]
	v_pk_mul_f32 v[16:17], v[16:17], v[140:141]
	v_pk_mul_f32 v[10:11], v[10:11], v[142:143]
	v_pk_mul_f32 v[12:13], v[12:13], v[144:145]
	v_cvt_pk_bf16_f32 v14, v14, v15
	v_cvt_pk_bf16_f32 v15, v16, v17
	v_cvt_pk_bf16_f32 v16, v10, v11
	v_cvt_pk_bf16_f32 v17, v12, v13
	global_store_dwordx4 v168, v[14:17], s[30:31] offset:256
	v_add_u32_e32 v168, 0x318000, v163
	v_pk_mul_f32 v[70:71], v[70:71], v[192:193] op_sel_hi:[1,0]
	v_pk_mul_f32 v[72:73], v[72:73], v[192:193] op_sel_hi:[1,0]
	v_pk_mul_f32 v[66:67], v[66:67], v[192:193] op_sel_hi:[1,0]
	v_pk_mul_f32 v[68:69], v[68:69], v[192:193] op_sel_hi:[1,0]
	v_pk_mul_f32 v[70:71], v[70:71], v[138:139]
	v_pk_mul_f32 v[72:73], v[72:73], v[140:141]
	v_pk_mul_f32 v[66:67], v[66:67], v[142:143]
	v_pk_mul_f32 v[68:69], v[68:69], v[144:145]
	v_cvt_pk_bf16_f32 v70, v70, v71
	v_cvt_pk_bf16_f32 v71, v72, v73
	v_cvt_pk_bf16_f32 v72, v66, v67
	v_cvt_pk_bf16_f32 v73, v68, v69
	global_store_dwordx4 v168, v[70:73], s[30:31]
	v_pk_mul_f32 v[6:7], v[6:7], v[192:193] op_sel:[0,1] op_sel_hi:[1,1]
	v_pk_mul_f32 v[8:9], v[8:9], v[192:193] op_sel:[0,1] op_sel_hi:[1,1]
	v_pk_mul_f32 v[2:3], v[2:3], v[192:193] op_sel:[0,1] op_sel_hi:[1,1]
	v_pk_mul_f32 v[4:5], v[4:5], v[192:193] op_sel:[0,1] op_sel_hi:[1,1]
	v_pk_mul_f32 v[6:7], v[6:7], v[138:139]
	v_pk_mul_f32 v[8:9], v[8:9], v[140:141]
	v_pk_mul_f32 v[2:3], v[2:3], v[142:143]
	v_pk_mul_f32 v[4:5], v[4:5], v[144:145]
	v_cvt_pk_bf16_f32 v6, v6, v7
	v_cvt_pk_bf16_f32 v7, v8, v9
	v_cvt_pk_bf16_f32 v8, v2, v3
	v_cvt_pk_bf16_f32 v9, v4, v5
	global_store_dwordx4 v168, v[6:9], s[30:31] offset:256
	s_branch .LBB0_1033
